# A1+E1+E2+E5+E6: rg_fix carry-in loop keeps 4 chunks' loads in flight; EpiResid 2x8 batched XB loads (no cache-warming loads)
# speedup vs baseline: 1.0150x; 1.0150x over previous
; __device__ __forceinline__ int tid_fresh() { int t = threadIdx.x; asm volatile("" : "+v"(t)); return t; }
; __device__ __forceinline__ void rg_fix_item(CArgs* a, int l, int item) {
;     const int tid = tid_fresh(), n = item & 7, c = (item >> 3) & 31, b = item >> 8;
;     const int ch = n * 128 + 4 * (tid & 31), tr = tid >> 5;
;     unsigned char* ws = a->ws; const float* PT = (const float*)(ws + WS_RGPT); const float* HT = (const float*)(ws + WS_RGHT);
;     f32x4 hin = (f32x4){0.f, 0.f, 0.f, 0.f};
;     for (int k = 0; k < c; ++k) hin = *(const f32x4*)(PT + ((size_t)b * NCH + k) * RGW + ch) * hin + *(const f32x4*)(HT + ((size_t)b * NCH + k) * RGW + ch);
.LBB0_1297:
	s_mov_b32 s100, 0xfff80000
	s_mov_b32 s101, -1
	v_lshl_add_u64 v[212:213], v[10:11], 0, s[48:49]
	v_lshl_add_u64 v[214:215], v[212:213], 0, s[48:49]
	v_lshl_add_u64 v[216:217], v[214:215], 0, s[48:49]
	v_lshl_add_u64 v[218:219], v[10:11], 0, s[100:101]
	v_lshl_add_u64 v[220:221], v[212:213], 0, s[100:101]
	v_lshl_add_u64 v[222:223], v[214:215], 0, s[100:101]
	v_lshl_add_u64 v[224:225], v[216:217], 0, s[100:101]
	global_load_dwordx4 v[160:163], v[218:219], off
	global_load_dwordx4 v[164:167], v[10:11], off
	global_load_dwordx4 v[168:171], v[220:221], off
	global_load_dwordx4 v[172:175], v[212:213], off
	global_load_dwordx4 v[176:179], v[222:223], off
	global_load_dwordx4 v[180:183], v[214:215], off
	global_load_dwordx4 v[184:187], v[224:225], off
	global_load_dwordx4 v[188:191], v[216:217], off
	v_lshl_add_u64 v[10:11], v[216:217], 0, s[48:49]
	s_waitcnt vmcnt(0)
	v_pk_fma_f32 v[6:7], v[6:7], v[162:163], v[166:167]
	v_pk_fma_f32 v[4:5], v[4:5], v[160:161], v[164:165]
	s_add_i32 s16, s16, -1
	s_cmp_eq_u32 s16, 0
	s_cbranch_scc1 .Lrgfix_done
	v_pk_fma_f32 v[6:7], v[6:7], v[170:171], v[174:175]
	v_pk_fma_f32 v[4:5], v[4:5], v[168:169], v[172:173]
	s_add_i32 s16, s16, -1
	s_cmp_eq_u32 s16, 0
	s_cbranch_scc1 .Lrgfix_done
	v_pk_fma_f32 v[6:7], v[6:7], v[178:179], v[182:183]
	v_pk_fma_f32 v[4:5], v[4:5], v[176:177], v[180:181]
	s_add_i32 s16, s16, -1
	s_cmp_eq_u32 s16, 0
	s_cbranch_scc1 .Lrgfix_done
	v_pk_fma_f32 v[6:7], v[6:7], v[186:187], v[190:191]
	v_pk_fma_f32 v[4:5], v[4:5], v[184:185], v[188:189]
	s_add_i32 s16, s16, -1
	s_cmp_eq_u32 s16, 0
	s_cbranch_scc0 .LBB0_1297
.Lrgfix_done:
	s_branch .LBB0_1300
